# P1 q/k epilogue: rmsnorm sum shuffles via v_permlane16_swap / v_permlane32_swap instead of ds_bpermute (bit-identical)
# speedup vs baseline: 1.1137x; 1.0003x over previous
.LBB0_436:
	s_and_b64 vcc, exec, s[6:7]
	s_cbranch_vccz .LBB0_435
	s_cmp_eq_u32 s25, 1
	s_cselect_b64 vcc, -1, 0
	s_and_b64 s[6:7], vcc, exec
	s_cselect_b32 s7, s81, s83
	s_cselect_b32 s6, s80, s82
	v_lshlrev_b32_e32 v132, 2, v154
	global_load_dwordx4 v[136:139], v132, s[6:7] offset:16
	global_load_dwordx4 v[140:143], v132, s[6:7]
	global_load_dwordx4 v[128:131], v132, s[6:7] offset:144
	s_nop 0
	global_load_dwordx4 v[132:135], v132, s[6:7] offset:128
	v_and_b32_e32 v168, 64, v178
	v_add_u32_e32 v181, 64, v168
	v_pk_mul_f32 v[168:169], v[126:127], v[126:127]
	v_pk_mul_f32 v[182:183], v[124:125], v[124:125]
	v_xor_b32_e32 v152, 16, v178
	v_pk_mov_b32 v[184:185], v[182:183], v[168:169] op_sel:[1,0]
	v_mov_b32_e32 v183, v169
	v_pk_add_f32 v[168:169], v[184:185], v[182:183]
	v_pk_mul_f32 v[182:183], v[122:123], v[122:123]
	v_pk_mul_f32 v[184:185], v[120:121], v[120:121]
	v_cndmask_b32_e32 v179, 1.0, v177, vcc
	v_cmp_lt_i32_e32 vcc, v152, v181
	v_pk_mov_b32 v[186:187], v[184:185], v[182:183] op_sel:[1,0]
	v_mov_b32_e32 v185, v183
	v_cndmask_b32_e32 v152, v178, v152, vcc
	v_pk_add_f32 v[182:183], v[186:187], v[184:185]
	v_lshlrev_b32_e32 v180, 2, v152
	v_mul_f32_e32 v152, v112, v112
	v_mul_f32_e32 v184, v113, v113
	v_pk_add_f32 v[168:169], v[168:169], v[168:169] op_sel:[0,1] op_sel_hi:[1,0]
	v_pk_add_f32 v[182:183], v[182:183], v[182:183] op_sel:[0,1] op_sel_hi:[1,0]
	v_mov_b32_e32 v169, v152
	v_mov_b32_e32 v183, v184
	v_mul_f32_e32 v152, v117, v117
	v_mul_f32_e32 v185, v114, v114
	v_pk_add_f32 v[168:169], v[168:169], v[182:183]
	v_pk_fma_f32 v[182:183], v[116:117], v[116:117], v[152:153] op_sel_hi:[1,1,0]
	v_mul_f32_e32 v152, v119, v119
	v_mul_f32_e32 v186, v115, v115
	v_mov_b32_e32 v183, v185
	v_pk_fma_f32 v[184:185], v[118:119], v[118:119], v[152:153] op_sel_hi:[1,1,0]
	s_lshl_b32 s6, s23, 25
	v_mov_b32_e32 v185, v186
	v_pk_add_f32 v[182:183], v[182:183], v[184:185]
	s_add_u32 s6, s3, s6
	v_pk_add_f32 v[168:169], v[168:169], v[182:183]
	s_addc_u32 s7, s66, 0
	v_add_f32_e32 v152, v168, v169
	v_mov_b32_e32 v168, v152
	s_nop 1
	v_permlane16_swap_b32_e32 v168, v152
	v_xor_b32_e32 v169, 32, v178
	v_cmp_lt_i32_e32 vcc, v169, v181
	s_lshl_b32 s23, s40, 9
	s_and_b32 s23, s23, 0x200
	v_cndmask_b32_e32 v169, v178, v169, vcc
	v_lshlrev_b32_e32 v181, 2, v169
	s_waitcnt lgkmcnt(0)
	v_add_f32_e32 v152, v152, v168
	v_mov_b32_e32 v168, v152
	s_nop 1
	v_permlane32_swap_b32_e32 v168, v152
	s_add_u32 s6, s6, s23
	s_addc_u32 s23, s7, 0
	s_add_u32 s26, s6, s68
	s_addc_u32 s27, s23, 0
	s_waitcnt lgkmcnt(0)
	v_add_f32_e32 v152, v152, v168
	v_fmamk_f32 v152, v152, 0x3c800000, v175
	v_mul_f32_e32 v168, 0x4f800000, v152
	v_cmp_gt_f32_e32 vcc, s69, v152
	s_nop 1
	v_cndmask_b32_e32 v152, v152, v168, vcc
	v_sqrt_f32_e32 v168, v152
	s_nop 0
	v_add_u32_e32 v169, -1, v168
	v_fma_f32 v182, -v169, v168, v152
	v_cmp_ge_f32_e64 s[6:7], 0, v182
	v_add_u32_e32 v182, 1, v168
	s_nop 0
	v_cndmask_b32_e64 v169, v168, v169, s[6:7]
	v_fma_f32 v168, -v182, v168, v152
	v_cmp_lt_f32_e64 s[6:7], 0, v168
	s_nop 1
	v_cndmask_b32_e64 v168, v169, v182, s[6:7]
	v_mul_f32_e32 v169, 0x37800000, v168
	v_cndmask_b32_e32 v168, v168, v169, vcc
	v_cmp_class_f32_e32 vcc, v152, v176
	s_nop 1
	v_cndmask_b32_e32 v182, v168, v152, vcc
	v_div_scale_f32 v183, s[6:7], v182, v182, v179
	v_rcp_f32_e32 v184, v183
	v_lshlrev_b32_e32 v152, 1, v154
	v_lshl_add_u64 v[168:169], s[26:27], 0, v[152:153]
	v_fma_f32 v152, -v183, v184, 1.0
	v_fmac_f32_e32 v184, v152, v184
	v_div_scale_f32 v152, vcc, v179, v182, v179
	v_mul_f32_e32 v185, v152, v184
	v_fma_f32 v186, -v183, v185, v152
	v_fmac_f32_e32 v185, v186, v184
	v_fma_f32 v152, -v183, v185, v152
	v_div_fmas_f32 v152, v152, v184, v185
	v_div_fixup_f32 v152, v152, v182, v179
	v_pk_mul_f32 v[124:125], v[124:125], v[152:153] op_sel_hi:[1,0]
	v_pk_mul_f32 v[120:121], v[120:121], v[152:153] op_sel_hi:[1,0]
	v_pk_mul_f32 v[126:127], v[126:127], v[152:153] op_sel_hi:[1,0]
	s_waitcnt vmcnt(0)
	v_pk_mul_f32 v[124:125], v[140:141], v[124:125]
	v_pk_mul_f32 v[122:123], v[122:123], v[152:153] op_sel_hi:[1,0]
	v_pk_mul_f32 v[120:121], v[136:137], v[120:121]
	v_pk_mul_f32 v[126:127], v[142:143], v[126:127]
	v_pk_mul_f32 v[182:183], v[138:139], v[122:123]
	v_cvt_pk_bf16_f32 v122, v124, v125
	v_cvt_pk_bf16_f32 v123, v126, v127
	v_cvt_pk_bf16_f32 v124, v120, v121
	v_lshlrev_b64 v[120:121], 10, v[166:167]
	v_cvt_pk_bf16_f32 v125, v182, v183
	v_lshl_add_u64 v[120:121], v[168:169], 0, v[120:121]
	global_store_dwordx4 v[120:121], v[122:125], off
	v_mul_f32_e32 v167, v98, v98
	v_pk_mul_f32 v[112:113], v[112:113], v[152:153] op_sel_hi:[1,0]
	v_pk_mul_f32 v[122:123], v[110:111], v[110:111]
	v_pk_mul_f32 v[124:125], v[108:109], v[108:109]
	v_pk_mul_f32 v[114:115], v[114:115], v[152:153] op_sel_hi:[1,0]
	v_pk_mov_b32 v[126:127], v[124:125], v[122:123] op_sel:[1,0]
	v_mov_b32_e32 v125, v123
	v_pk_add_f32 v[122:123], v[126:127], v[124:125]
	v_pk_mul_f32 v[124:125], v[106:107], v[106:107]
	v_pk_mul_f32 v[126:127], v[104:105], v[104:105]
	v_pk_add_f32 v[122:123], v[122:123], v[122:123] op_sel:[0,1] op_sel_hi:[1,0]
	v_pk_mov_b32 v[182:183], v[126:127], v[124:125] op_sel:[1,0]
	v_mov_b32_e32 v127, v125
	v_pk_add_f32 v[124:125], v[182:183], v[126:127]
	v_mul_f32_e32 v126, v96, v96
	v_mul_f32_e32 v127, v97, v97
	v_pk_add_f32 v[124:125], v[124:125], v[124:125] op_sel:[0,1] op_sel_hi:[1,0]
	v_mov_b32_e32 v123, v126
	v_mov_b32_e32 v125, v127
	v_pk_add_f32 v[122:123], v[122:123], v[124:125]
	v_mul_f32_e32 v124, v101, v101
	v_mul_f32_e32 v126, v103, v103
	v_mul_f32_e32 v182, v99, v99
	v_pk_fma_f32 v[124:125], v[100:101], v[100:101], v[124:125] op_sel_hi:[1,1,0]
	v_pk_fma_f32 v[126:127], v[102:103], v[102:103], v[126:127] op_sel_hi:[1,1,0]
	v_mov_b32_e32 v125, v167
	v_mov_b32_e32 v127, v182
	v_pk_add_f32 v[124:125], v[124:125], v[126:127]
	v_pk_mul_f32 v[116:117], v[116:117], v[152:153] op_sel_hi:[1,0]
	v_pk_add_f32 v[122:123], v[122:123], v[124:125]
	v_pk_mul_f32 v[118:119], v[118:119], v[152:153] op_sel_hi:[1,0]
	v_add_f32_e32 v122, v122, v123
	v_mov_b32_e32 v123, v122
	s_nop 1
	v_permlane16_swap_b32_e32 v123, v122
	v_pk_mul_f32 v[118:119], v[134:135], v[118:119]
	v_pk_mul_f32 v[116:117], v[132:133], v[116:117]
	s_waitcnt lgkmcnt(0)
	v_add_f32_e32 v124, v122, v123
	v_mov_b32_e32 v125, v124
	s_nop 1
	v_permlane32_swap_b32_e32 v125, v124
	v_pk_mul_f32 v[122:123], v[130:131], v[114:115]
	v_pk_mul_f32 v[114:115], v[128:129], v[112:113]
	s_waitcnt lgkmcnt(0)
	v_add_f32_e32 v112, v124, v125
	v_fmamk_f32 v112, v112, 0x3c800000, v175
	v_mul_f32_e32 v113, 0x4f800000, v112
	v_cmp_gt_f32_e32 vcc, s69, v112
	s_nop 1
	v_cndmask_b32_e32 v124, v112, v113, vcc
	v_sqrt_f32_e32 v125, v124
	v_cvt_pk_bf16_f32 v112, v116, v117
	v_cvt_pk_bf16_f32 v113, v118, v119
	v_cvt_pk_bf16_f32 v114, v114, v115
	s_nop 0
	v_add_u32_e32 v115, -1, v125
	v_fma_f32 v116, -v115, v125, v124
	v_cmp_ge_f32_e64 s[6:7], 0, v116
	v_add_u32_e32 v116, 1, v125
	v_fma_f32 v117, -v116, v125, v124
	v_cndmask_b32_e64 v115, v125, v115, s[6:7]
	v_cmp_lt_f32_e64 s[6:7], 0, v117
	s_nop 1
	v_cndmask_b32_e64 v115, v115, v116, s[6:7]
	v_mul_f32_e32 v116, 0x37800000, v115
	v_cndmask_b32_e32 v115, v115, v116, vcc
	v_cmp_class_f32_e32 vcc, v124, v176
	s_nop 1
	v_cndmask_b32_e32 v116, v115, v124, vcc
	v_div_scale_f32 v117, s[6:7], v116, v116, v179
	v_rcp_f32_e32 v118, v117
	v_cvt_pk_bf16_f32 v115, v122, v123
	global_store_dwordx4 v[120:121], v[112:115], off offset:64
	s_nop 1
	v_fma_f32 v113, -v117, v118, 1.0
	v_fmac_f32_e32 v118, v113, v118
	v_div_scale_f32 v113, vcc, v179, v116, v179
	v_mul_f32_e32 v114, v113, v118
	v_fma_f32 v115, -v117, v114, v113
	v_fmac_f32_e32 v114, v115, v118
	v_fma_f32 v113, -v117, v114, v113
	v_div_fmas_f32 v113, v113, v118, v114
	v_div_fixup_f32 v114, v113, v116, v179
	v_or_b32_e32 v112, 16, v166
	v_pk_mul_f32 v[108:109], v[108:109], v[114:115] op_sel_hi:[1,0]
	v_pk_mul_f32 v[104:105], v[104:105], v[114:115] op_sel_hi:[1,0]
	v_pk_mul_f32 v[108:109], v[140:141], v[108:109]
	v_pk_mul_f32 v[106:107], v[106:107], v[114:115] op_sel_hi:[1,0]
	v_ashrrev_i32_e32 v113, 31, v112
	v_pk_mul_f32 v[110:111], v[110:111], v[114:115] op_sel_hi:[1,0]
	v_pk_mul_f32 v[116:117], v[138:139], v[106:107]
	v_pk_mul_f32 v[106:107], v[136:137], v[104:105]
	v_cvt_pk_bf16_f32 v104, v108, v109
	v_lshlrev_b64 v[108:109], 10, v[112:113]
	v_pk_mul_f32 v[110:111], v[142:143], v[110:111]
	v_lshl_add_u64 v[108:109], v[168:169], 0, v[108:109]
	v_cvt_pk_bf16_f32 v105, v110, v111
	v_cvt_pk_bf16_f32 v106, v106, v107
	v_cvt_pk_bf16_f32 v107, v116, v117
	global_store_dwordx4 v[108:109], v[104:107], off
	v_pk_mul_f32 v[96:97], v[96:97], v[114:115] op_sel_hi:[1,0]
	v_pk_mul_f32 v[98:99], v[98:99], v[114:115] op_sel_hi:[1,0]
	v_pk_mul_f32 v[104:105], v[94:95], v[94:95]
	v_pk_mul_f32 v[106:107], v[92:93], v[92:93]
	v_pk_mul_f32 v[100:101], v[100:101], v[114:115] op_sel_hi:[1,0]
	v_pk_mov_b32 v[110:111], v[106:107], v[104:105] op_sel:[1,0]
	v_mov_b32_e32 v107, v105
	v_pk_add_f32 v[104:105], v[110:111], v[106:107]
	v_pk_mul_f32 v[106:107], v[90:91], v[90:91]
	v_pk_mul_f32 v[110:111], v[88:89], v[88:89]
	v_pk_add_f32 v[104:105], v[104:105], v[104:105] op_sel:[0,1] op_sel_hi:[1,0]
	v_pk_mov_b32 v[112:113], v[110:111], v[106:107] op_sel:[1,0]
	v_mov_b32_e32 v111, v107
	v_pk_add_f32 v[106:107], v[112:113], v[110:111]
	v_mul_f32_e32 v110, v80, v80
	v_mul_f32_e32 v111, v81, v81
	v_pk_add_f32 v[106:107], v[106:107], v[106:107] op_sel:[0,1] op_sel_hi:[1,0]
	v_mov_b32_e32 v105, v110
	v_mov_b32_e32 v107, v111
	v_pk_add_f32 v[104:105], v[104:105], v[106:107]
	v_mul_f32_e32 v106, v85, v85
	v_mul_f32_e32 v110, v87, v87
	v_mul_f32_e32 v112, v82, v82
	v_mul_f32_e32 v113, v83, v83
	v_pk_fma_f32 v[106:107], v[84:85], v[84:85], v[106:107] op_sel_hi:[1,1,0]
	v_pk_fma_f32 v[110:111], v[86:87], v[86:87], v[110:111] op_sel_hi:[1,1,0]
	v_mov_b32_e32 v107, v112
	v_mov_b32_e32 v111, v113
	v_pk_add_f32 v[106:107], v[106:107], v[110:111]
	v_pk_mul_f32 v[102:103], v[102:103], v[114:115] op_sel_hi:[1,0]
	v_pk_add_f32 v[104:105], v[104:105], v[106:107]
	v_pk_mul_f32 v[102:103], v[134:135], v[102:103]
	v_add_f32_e32 v104, v104, v105
	v_mov_b32_e32 v105, v104
	s_nop 1
	v_permlane16_swap_b32_e32 v105, v104
	v_pk_mul_f32 v[100:101], v[132:133], v[100:101]
	s_waitcnt lgkmcnt(0)
	v_add_f32_e32 v106, v104, v105
	v_mov_b32_e32 v107, v106
	s_nop 1
	v_permlane32_swap_b32_e32 v107, v106
	v_pk_mul_f32 v[104:105], v[130:131], v[98:99]
	v_pk_mul_f32 v[98:99], v[128:129], v[96:97]
	s_waitcnt lgkmcnt(0)
	v_add_f32_e32 v96, v106, v107
	v_fmamk_f32 v96, v96, 0x3c800000, v175
	v_mul_f32_e32 v97, 0x4f800000, v96
	v_cmp_gt_f32_e32 vcc, s69, v96
	s_nop 1
	v_cndmask_b32_e32 v106, v96, v97, vcc
	v_sqrt_f32_e32 v107, v106
	v_cvt_pk_bf16_f32 v96, v100, v101
	v_cvt_pk_bf16_f32 v97, v102, v103
	v_cvt_pk_bf16_f32 v98, v98, v99
	s_nop 0
	v_add_u32_e32 v99, -1, v107
	v_fma_f32 v100, -v99, v107, v106
	v_cmp_ge_f32_e64 s[6:7], 0, v100
	v_add_u32_e32 v100, 1, v107
	v_fma_f32 v101, -v100, v107, v106
	v_cndmask_b32_e64 v99, v107, v99, s[6:7]
	v_cmp_lt_f32_e64 s[6:7], 0, v101
	s_nop 1
	v_cndmask_b32_e64 v99, v99, v100, s[6:7]
	v_mul_f32_e32 v100, 0x37800000, v99
	v_cndmask_b32_e32 v99, v99, v100, vcc
	v_cmp_class_f32_e32 vcc, v106, v176
	s_nop 1
	v_cndmask_b32_e32 v100, v99, v106, vcc
	v_div_scale_f32 v101, s[6:7], v100, v100, v179
	v_rcp_f32_e32 v102, v101
	v_cvt_pk_bf16_f32 v99, v104, v105
	global_store_dwordx4 v[108:109], v[96:99], off offset:64
	s_nop 1
	v_fma_f32 v97, -v101, v102, 1.0
	v_fmac_f32_e32 v102, v97, v102
	v_div_scale_f32 v97, vcc, v179, v100, v179
	v_mul_f32_e32 v98, v97, v102
	v_fma_f32 v99, -v101, v98, v97
	v_fmac_f32_e32 v98, v99, v102
	v_fma_f32 v97, -v101, v98, v97
	v_div_fmas_f32 v97, v97, v102, v98
	v_div_fixup_f32 v98, v97, v100, v179
	v_or_b32_e32 v96, 32, v166
	v_pk_mul_f32 v[92:93], v[92:93], v[98:99] op_sel_hi:[1,0]
	v_pk_mul_f32 v[88:89], v[88:89], v[98:99] op_sel_hi:[1,0]
	v_pk_mul_f32 v[92:93], v[140:141], v[92:93]
	v_pk_mul_f32 v[90:91], v[90:91], v[98:99] op_sel_hi:[1,0]
	v_ashrrev_i32_e32 v97, 31, v96
	v_pk_mul_f32 v[94:95], v[94:95], v[98:99] op_sel_hi:[1,0]
	v_pk_mul_f32 v[100:101], v[138:139], v[90:91]
	v_pk_mul_f32 v[90:91], v[136:137], v[88:89]
	v_cvt_pk_bf16_f32 v88, v92, v93
	v_lshlrev_b64 v[92:93], 10, v[96:97]
	v_pk_mul_f32 v[94:95], v[142:143], v[94:95]
	v_lshl_add_u64 v[92:93], v[168:169], 0, v[92:93]
	v_cvt_pk_bf16_f32 v89, v94, v95
	v_cvt_pk_bf16_f32 v90, v90, v91
	v_cvt_pk_bf16_f32 v91, v100, v101
	global_store_dwordx4 v[92:93], v[88:91], off
	v_pk_mul_f32 v[80:81], v[80:81], v[98:99] op_sel_hi:[1,0]
	v_pk_mul_f32 v[82:83], v[82:83], v[98:99] op_sel_hi:[1,0]
	v_pk_mul_f32 v[88:89], v[78:79], v[78:79]
	v_pk_mul_f32 v[90:91], v[76:77], v[76:77]
	v_pk_mul_f32 v[84:85], v[84:85], v[98:99] op_sel_hi:[1,0]
	v_pk_mov_b32 v[94:95], v[90:91], v[88:89] op_sel:[1,0]
	v_mov_b32_e32 v91, v89
	v_pk_add_f32 v[88:89], v[94:95], v[90:91]
	v_pk_mul_f32 v[90:91], v[74:75], v[74:75]
	v_pk_mul_f32 v[94:95], v[72:73], v[72:73]
	v_pk_add_f32 v[88:89], v[88:89], v[88:89] op_sel:[0,1] op_sel_hi:[1,0]
	v_pk_mov_b32 v[96:97], v[94:95], v[90:91] op_sel:[1,0]
	v_mov_b32_e32 v95, v91
	v_pk_add_f32 v[90:91], v[96:97], v[94:95]
	v_mul_f32_e32 v94, v64, v64
	v_mul_f32_e32 v95, v65, v65
	v_pk_add_f32 v[90:91], v[90:91], v[90:91] op_sel:[0,1] op_sel_hi:[1,0]
	v_mov_b32_e32 v89, v94
	v_mov_b32_e32 v91, v95
	v_pk_add_f32 v[88:89], v[88:89], v[90:91]
	v_mul_f32_e32 v90, v69, v69
	v_mul_f32_e32 v94, v71, v71
	v_mul_f32_e32 v96, v66, v66
	v_mul_f32_e32 v97, v67, v67
	v_pk_fma_f32 v[90:91], v[68:69], v[68:69], v[90:91] op_sel_hi:[1,1,0]
	v_pk_fma_f32 v[94:95], v[70:71], v[70:71], v[94:95] op_sel_hi:[1,1,0]
	v_mov_b32_e32 v91, v96
	v_mov_b32_e32 v95, v97
	v_pk_add_f32 v[90:91], v[90:91], v[94:95]
	v_pk_mul_f32 v[86:87], v[86:87], v[98:99] op_sel_hi:[1,0]
	v_pk_add_f32 v[88:89], v[88:89], v[90:91]
	v_pk_mul_f32 v[86:87], v[134:135], v[86:87]
	v_add_f32_e32 v88, v88, v89
	v_mov_b32_e32 v89, v88
	s_nop 1
	v_permlane16_swap_b32_e32 v89, v88
	v_pk_mul_f32 v[84:85], v[132:133], v[84:85]
	s_waitcnt lgkmcnt(0)
	v_add_f32_e32 v90, v88, v89
	v_mov_b32_e32 v91, v90
	s_nop 1
	v_permlane32_swap_b32_e32 v91, v90
	v_pk_mul_f32 v[88:89], v[130:131], v[82:83]
	v_pk_mul_f32 v[82:83], v[128:129], v[80:81]
	s_waitcnt lgkmcnt(0)
	v_add_f32_e32 v80, v90, v91
	v_fmamk_f32 v80, v80, 0x3c800000, v175
	v_mul_f32_e32 v81, 0x4f800000, v80
	v_cmp_gt_f32_e32 vcc, s69, v80
	s_nop 1
	v_cndmask_b32_e32 v90, v80, v81, vcc
	v_sqrt_f32_e32 v91, v90
	v_cvt_pk_bf16_f32 v80, v84, v85
	v_cvt_pk_bf16_f32 v81, v86, v87
	v_cvt_pk_bf16_f32 v82, v82, v83
	s_nop 0
	v_add_u32_e32 v83, -1, v91
	v_fma_f32 v84, -v83, v91, v90
	v_cmp_ge_f32_e64 s[6:7], 0, v84
	v_add_u32_e32 v84, 1, v91
	v_fma_f32 v85, -v84, v91, v90
	v_cndmask_b32_e64 v83, v91, v83, s[6:7]
	v_cmp_lt_f32_e64 s[6:7], 0, v85
	s_nop 1
	v_cndmask_b32_e64 v83, v83, v84, s[6:7]
	v_mul_f32_e32 v84, 0x37800000, v83
	v_cndmask_b32_e32 v83, v83, v84, vcc
	v_cmp_class_f32_e32 vcc, v90, v176
	s_nop 1
	v_cndmask_b32_e32 v84, v83, v90, vcc
	v_div_scale_f32 v85, s[6:7], v84, v84, v179
	v_rcp_f32_e32 v86, v85
	v_cvt_pk_bf16_f32 v83, v88, v89
	global_store_dwordx4 v[92:93], v[80:83], off offset:64
	s_nop 1
	v_fma_f32 v81, -v85, v86, 1.0
	v_fmac_f32_e32 v86, v81, v86
	v_div_scale_f32 v81, vcc, v179, v84, v179
	v_mul_f32_e32 v82, v81, v86
	v_fma_f32 v83, -v85, v82, v81
	v_fmac_f32_e32 v82, v83, v86
	v_fma_f32 v81, -v85, v82, v81
	v_div_fmas_f32 v81, v81, v86, v82
	v_div_fixup_f32 v82, v81, v84, v179
	v_or_b32_e32 v80, 48, v166
	v_pk_mul_f32 v[76:77], v[76:77], v[82:83] op_sel_hi:[1,0]
	v_pk_mul_f32 v[78:79], v[78:79], v[82:83] op_sel_hi:[1,0]
	v_pk_mul_f32 v[76:77], v[140:141], v[76:77]
	v_pk_mul_f32 v[78:79], v[142:143], v[78:79]
	v_pk_mul_f32 v[72:73], v[72:73], v[82:83] op_sel_hi:[1,0]
	v_pk_mul_f32 v[74:75], v[74:75], v[82:83] op_sel_hi:[1,0]
	v_ashrrev_i32_e32 v81, 31, v80
	v_pk_mul_f32 v[84:85], v[138:139], v[74:75]
	v_pk_mul_f32 v[74:75], v[136:137], v[72:73]
	v_cvt_pk_bf16_f32 v72, v76, v77
	v_cvt_pk_bf16_f32 v73, v78, v79
	v_lshlrev_b64 v[76:77], 10, v[80:81]
	v_pk_mul_f32 v[78:79], v[62:63], v[62:63]
	v_pk_mul_f32 v[80:81], v[60:61], v[60:61]
	v_cvt_pk_bf16_f32 v74, v74, v75
	v_cvt_pk_bf16_f32 v75, v84, v85
	v_mul_f32_e32 v83, v48, v48
	v_pk_mov_b32 v[84:85], v[80:81], v[78:79] op_sel:[1,0]
	v_mov_b32_e32 v81, v79
	v_pk_add_f32 v[78:79], v[84:85], v[80:81]
	v_pk_mul_f32 v[80:81], v[58:59], v[58:59]
	v_pk_mul_f32 v[84:85], v[56:57], v[56:57]
	v_pk_add_f32 v[78:79], v[78:79], v[78:79] op_sel:[0,1] op_sel_hi:[1,0]
	v_pk_mov_b32 v[86:87], v[84:85], v[80:81] op_sel:[1,0]
	v_mov_b32_e32 v85, v81
	v_pk_add_f32 v[80:81], v[86:87], v[84:85]
	v_mul_f32_e32 v84, v49, v49
	v_pk_add_f32 v[80:81], v[80:81], v[80:81] op_sel:[0,1] op_sel_hi:[1,0]
	v_mov_b32_e32 v79, v83
	v_mov_b32_e32 v81, v84
	v_pk_add_f32 v[78:79], v[78:79], v[80:81]
	v_mul_f32_e32 v80, v53, v53
	v_mul_f32_e32 v85, v50, v50
	v_pk_fma_f32 v[80:81], v[52:53], v[52:53], v[80:81] op_sel_hi:[1,1,0]
	v_mul_f32_e32 v84, v55, v55
	v_mul_f32_e32 v86, v51, v51
	v_mov_b32_e32 v81, v85
	v_pk_fma_f32 v[84:85], v[54:55], v[54:55], v[84:85] op_sel_hi:[1,1,0]
	v_lshl_add_u64 v[76:77], v[168:169], 0, v[76:77]
	v_mov_b32_e32 v85, v86
	v_pk_add_f32 v[80:81], v[80:81], v[84:85]
	global_store_dwordx4 v[76:77], v[72:75], off
	v_pk_add_f32 v[78:79], v[78:79], v[80:81]
	v_pk_mul_f32 v[66:67], v[66:67], v[82:83] op_sel_hi:[1,0]
	v_add_f32_e32 v78, v78, v79
	v_mov_b32_e32 v79, v78
	s_nop 1
	v_permlane16_swap_b32_e32 v79, v78
	v_pk_mul_f32 v[72:73], v[130:131], v[66:67]
	v_pk_mul_f32 v[68:69], v[68:69], v[82:83] op_sel_hi:[1,0]
	v_pk_mul_f32 v[64:65], v[64:65], v[82:83] op_sel_hi:[1,0]
	v_pk_mul_f32 v[68:69], v[132:133], v[68:69]
	s_waitcnt lgkmcnt(0)
	v_add_f32_e32 v74, v78, v79
	v_mov_b32_e32 v75, v74
	s_nop 1
	v_permlane32_swap_b32_e32 v75, v74
	v_pk_mul_f32 v[70:71], v[70:71], v[82:83] op_sel_hi:[1,0]
	s_waitcnt lgkmcnt(0)
	v_add_f32_e32 v66, v74, v75
	v_fmamk_f32 v66, v66, 0x3c800000, v175
	v_mul_f32_e32 v67, 0x4f800000, v66
	v_cmp_gt_f32_e32 vcc, s69, v66
	v_pk_mul_f32 v[70:71], v[134:135], v[70:71]
	s_nop 0
	v_cndmask_b32_e32 v74, v66, v67, vcc
	v_sqrt_f32_e32 v75, v74
	v_pk_mul_f32 v[66:67], v[128:129], v[64:65]
	v_cvt_pk_bf16_f32 v64, v68, v69
	v_cvt_pk_bf16_f32 v65, v70, v71
	v_add_u32_e32 v68, -1, v75
	v_fma_f32 v69, -v68, v75, v74
	v_cmp_ge_f32_e64 s[6:7], 0, v69
	v_add_u32_e32 v69, 1, v75
	v_fma_f32 v70, -v69, v75, v74
	v_cndmask_b32_e64 v68, v75, v68, s[6:7]
	v_cmp_lt_f32_e64 s[6:7], 0, v70
	v_cvt_pk_bf16_f32 v66, v66, v67
	v_cvt_pk_bf16_f32 v67, v72, v73
	global_store_dwordx4 v[76:77], v[64:67], off offset:64
	s_nop 0
	v_cndmask_b32_e64 v68, v68, v69, s[6:7]
	v_mul_f32_e32 v69, 0x37800000, v68
	v_cndmask_b32_e32 v68, v68, v69, vcc
	v_cmp_class_f32_e32 vcc, v74, v176
	s_nop 1
	v_cndmask_b32_e32 v68, v68, v74, vcc
	v_div_scale_f32 v69, s[6:7], v68, v68, v179
	v_rcp_f32_e32 v70, v69
	s_mov_b64 s[6:7], 0x20000
	v_fma_f32 v64, -v69, v70, 1.0
	v_fmac_f32_e32 v70, v64, v70
	v_div_scale_f32 v64, vcc, v179, v68, v179
	v_mul_f32_e32 v65, v64, v70
	v_fma_f32 v66, -v69, v65, v64
	v_fmac_f32_e32 v65, v66, v70
	v_fma_f32 v64, -v69, v65, v64
	v_div_fmas_f32 v64, v64, v70, v65
	v_div_fixup_f32 v64, v64, v68, v179
	v_pk_mul_f32 v[56:57], v[56:57], v[64:65] op_sel_hi:[1,0]
	v_pk_mul_f32 v[58:59], v[58:59], v[64:65] op_sel_hi:[1,0]
	v_pk_mul_f32 v[60:61], v[60:61], v[64:65] op_sel_hi:[1,0]
	v_pk_mul_f32 v[62:63], v[62:63], v[64:65] op_sel_hi:[1,0]
	v_pk_mul_f32 v[66:67], v[138:139], v[58:59]
	v_pk_mul_f32 v[58:59], v[136:137], v[56:57]
	v_pk_mul_f32 v[62:63], v[142:143], v[62:63]
	v_pk_mul_f32 v[60:61], v[140:141], v[60:61]
	v_pk_mul_f32 v[68:69], v[44:45], v[44:45]
	v_cvt_pk_bf16_f32 v56, v60, v61
	v_cvt_pk_bf16_f32 v57, v62, v63
	v_cvt_pk_bf16_f32 v58, v58, v59
	v_cvt_pk_bf16_f32 v59, v66, v67
	v_pk_mul_f32 v[66:67], v[46:47], v[46:47]
	v_mul_f32_e32 v65, v32, v32
	v_pk_mov_b32 v[70:71], v[68:69], v[66:67] op_sel:[1,0]
	v_mov_b32_e32 v69, v67
	v_pk_add_f32 v[66:67], v[70:71], v[68:69]
	v_pk_mul_f32 v[68:69], v[42:43], v[42:43]
	v_pk_mul_f32 v[70:71], v[40:41], v[40:41]
	v_pk_add_f32 v[66:67], v[66:67], v[66:67] op_sel:[0,1] op_sel_hi:[1,0]
	v_pk_mov_b32 v[72:73], v[70:71], v[68:69] op_sel:[1,0]
	v_mov_b32_e32 v71, v69
	v_pk_add_f32 v[68:69], v[72:73], v[70:71]
	v_mul_f32_e32 v70, v33, v33
	v_pk_add_f32 v[68:69], v[68:69], v[68:69] op_sel:[0,1] op_sel_hi:[1,0]
	v_mov_b32_e32 v67, v65
	v_mov_b32_e32 v69, v70
	v_pk_add_f32 v[66:67], v[66:67], v[68:69]
	v_mul_f32_e32 v68, v37, v37
	v_mul_f32_e32 v71, v34, v34
	v_pk_fma_f32 v[68:69], v[36:37], v[36:37], v[68:69] op_sel_hi:[1,1,0]
	v_mul_f32_e32 v70, v39, v39
	v_mul_f32_e32 v72, v35, v35
	v_mov_b32_e32 v69, v71
	v_pk_fma_f32 v[70:71], v[38:39], v[38:39], v[70:71] op_sel_hi:[1,1,0]
	v_lshl_add_u64 v[60:61], v[120:121], 0, s[6:7]
	v_mov_b32_e32 v71, v72
	v_pk_add_f32 v[68:69], v[68:69], v[70:71]
	s_mov_b32 s6, 0x20000
	v_pk_add_f32 v[66:67], v[66:67], v[68:69]
	v_add_co_u32_e32 v62, vcc, s6, v120
	v_add_f32_e32 v65, v66, v67
	v_mov_b32_e32 v66, v65
	s_nop 1
	v_permlane16_swap_b32_e32 v66, v65
	v_addc_co_u32_e32 v63, vcc, 0, v121, vcc
	global_store_dwordx4 v[62:63], v[56:59], off
	v_pk_mul_f32 v[50:51], v[50:51], v[64:65] op_sel_hi:[1,0]
	v_pk_mul_f32 v[52:53], v[52:53], v[64:65] op_sel_hi:[1,0]
	s_waitcnt lgkmcnt(0)
	v_add_f32_e32 v58, v65, v66
	v_mov_b32_e32 v59, v58
	s_nop 1
	v_permlane32_swap_b32_e32 v59, v58
	v_pk_mul_f32 v[56:57], v[130:131], v[50:51]
	v_pk_mul_f32 v[52:53], v[132:133], v[52:53]
	v_pk_mul_f32 v[48:49], v[48:49], v[64:65] op_sel_hi:[1,0]
	v_pk_mul_f32 v[54:55], v[54:55], v[64:65] op_sel_hi:[1,0]
	s_waitcnt lgkmcnt(0)
	v_add_f32_e32 v50, v58, v59
	v_fmamk_f32 v50, v50, 0x3c800000, v175
	v_mul_f32_e32 v51, 0x4f800000, v50
	v_cmp_gt_f32_e32 vcc, s69, v50
	v_pk_mul_f32 v[54:55], v[134:135], v[54:55]
	s_nop 0
	v_cndmask_b32_e32 v58, v50, v51, vcc
	v_sqrt_f32_e32 v59, v58
	v_pk_mul_f32 v[50:51], v[128:129], v[48:49]
	v_cvt_pk_bf16_f32 v48, v52, v53
	v_cvt_pk_bf16_f32 v49, v54, v55
	v_add_u32_e32 v52, -1, v59
	v_fma_f32 v53, -v52, v59, v58
	v_cmp_ge_f32_e64 s[6:7], 0, v53
	v_add_u32_e32 v53, 1, v59
	v_fma_f32 v54, -v53, v59, v58
	v_cndmask_b32_e64 v52, v59, v52, s[6:7]
	v_cmp_lt_f32_e64 s[6:7], 0, v54
	v_cvt_pk_bf16_f32 v50, v50, v51
	v_cvt_pk_bf16_f32 v51, v56, v57
	global_store_dwordx4 v[60:61], v[48:51], off offset:64
	s_nop 0
	v_cndmask_b32_e64 v52, v52, v53, s[6:7]
	v_mul_f32_e32 v53, 0x37800000, v52
	v_cndmask_b32_e32 v52, v52, v53, vcc
	v_cmp_class_f32_e32 vcc, v58, v176
	s_nop 1
	v_cndmask_b32_e32 v52, v52, v58, vcc
	v_div_scale_f32 v53, s[6:7], v52, v52, v179
	v_rcp_f32_e32 v54, v53
	s_mov_b64 s[6:7], 0x24000
	v_fma_f32 v48, -v53, v54, 1.0
	v_fmac_f32_e32 v54, v48, v54
	v_div_scale_f32 v48, vcc, v179, v52, v179
	v_mul_f32_e32 v49, v48, v54
	v_fma_f32 v50, -v53, v49, v48
	v_fmac_f32_e32 v49, v50, v54
	v_fma_f32 v48, -v53, v49, v48
	v_div_fmas_f32 v48, v48, v54, v49
	v_div_fixup_f32 v48, v48, v52, v179
	v_pk_mul_f32 v[40:41], v[40:41], v[48:49] op_sel_hi:[1,0]
	v_pk_mul_f32 v[42:43], v[42:43], v[48:49] op_sel_hi:[1,0]
	v_pk_mul_f32 v[44:45], v[44:45], v[48:49] op_sel_hi:[1,0]
	v_pk_mul_f32 v[46:47], v[46:47], v[48:49] op_sel_hi:[1,0]
	v_pk_mul_f32 v[50:51], v[138:139], v[42:43]
	v_pk_mul_f32 v[42:43], v[136:137], v[40:41]
	v_pk_mul_f32 v[46:47], v[142:143], v[46:47]
	v_pk_mul_f32 v[44:45], v[140:141], v[44:45]
	v_pk_mul_f32 v[52:53], v[28:29], v[28:29]
	v_cvt_pk_bf16_f32 v40, v44, v45
	v_cvt_pk_bf16_f32 v41, v46, v47
	v_cvt_pk_bf16_f32 v42, v42, v43
	v_cvt_pk_bf16_f32 v43, v50, v51
	v_pk_mul_f32 v[50:51], v[30:31], v[30:31]
	v_mul_f32_e32 v49, v16, v16
	v_pk_mov_b32 v[54:55], v[52:53], v[50:51] op_sel:[1,0]
	v_mov_b32_e32 v53, v51
	v_pk_add_f32 v[50:51], v[54:55], v[52:53]
	v_pk_mul_f32 v[52:53], v[26:27], v[26:27]
	v_pk_mul_f32 v[54:55], v[24:25], v[24:25]
	v_pk_add_f32 v[50:51], v[50:51], v[50:51] op_sel:[0,1] op_sel_hi:[1,0]
	v_pk_mov_b32 v[56:57], v[54:55], v[52:53] op_sel:[1,0]
	v_mov_b32_e32 v55, v53
	v_pk_add_f32 v[52:53], v[56:57], v[54:55]
	v_mul_f32_e32 v54, v17, v17
	v_pk_add_f32 v[52:53], v[52:53], v[52:53] op_sel:[0,1] op_sel_hi:[1,0]
	v_mov_b32_e32 v51, v49
	v_mov_b32_e32 v53, v54
	v_pk_add_f32 v[50:51], v[50:51], v[52:53]
	v_mul_f32_e32 v52, v21, v21
	v_mul_f32_e32 v55, v18, v18
	v_pk_fma_f32 v[52:53], v[20:21], v[20:21], v[52:53] op_sel_hi:[1,1,0]
	v_mul_f32_e32 v54, v23, v23
	v_mul_f32_e32 v56, v19, v19
	v_mov_b32_e32 v53, v55
	v_pk_fma_f32 v[54:55], v[22:23], v[22:23], v[54:55] op_sel_hi:[1,1,0]
	v_add_co_u32_e32 v46, vcc, s70, v120
	v_mov_b32_e32 v55, v56
	v_pk_add_f32 v[52:53], v[52:53], v[54:55]
	v_addc_co_u32_e32 v47, vcc, 0, v121, vcc
	v_pk_add_f32 v[50:51], v[50:51], v[52:53]
	global_store_dwordx4 v[46:47], v[40:43], off
	v_add_f32_e32 v49, v50, v51
	v_mov_b32_e32 v50, v49
	s_nop 1
	v_permlane16_swap_b32_e32 v50, v49
	v_pk_mul_f32 v[34:35], v[34:35], v[48:49] op_sel_hi:[1,0]
	v_pk_mul_f32 v[36:37], v[36:37], v[48:49] op_sel_hi:[1,0]
	v_pk_mul_f32 v[40:41], v[130:131], v[34:35]
	v_pk_mul_f32 v[36:37], v[132:133], v[36:37]
	s_waitcnt lgkmcnt(0)
	v_add_f32_e32 v42, v49, v50
	v_mov_b32_e32 v43, v42
	s_nop 1
	v_permlane32_swap_b32_e32 v43, v42
	v_pk_mul_f32 v[32:33], v[32:33], v[48:49] op_sel_hi:[1,0]
	v_pk_mul_f32 v[38:39], v[38:39], v[48:49] op_sel_hi:[1,0]
	v_lshl_add_u64 v[44:45], v[120:121], 0, s[6:7]
	v_pk_mul_f32 v[38:39], v[134:135], v[38:39]
	s_waitcnt lgkmcnt(0)
	v_add_f32_e32 v34, v42, v43
	v_fmamk_f32 v34, v34, 0x3c800000, v175
	v_mul_f32_e32 v35, 0x4f800000, v34
	v_cmp_gt_f32_e32 vcc, s69, v34
	s_nop 1
	v_cndmask_b32_e32 v42, v34, v35, vcc
	v_sqrt_f32_e32 v43, v42
	v_pk_mul_f32 v[34:35], v[128:129], v[32:33]
	v_cvt_pk_bf16_f32 v32, v36, v37
	v_cvt_pk_bf16_f32 v33, v38, v39
	v_add_u32_e32 v36, -1, v43
	v_fma_f32 v37, -v36, v43, v42
	v_cmp_ge_f32_e64 s[6:7], 0, v37
	v_add_u32_e32 v37, 1, v43
	v_fma_f32 v38, -v37, v43, v42
	v_cndmask_b32_e64 v36, v43, v36, s[6:7]
	v_cmp_lt_f32_e64 s[6:7], 0, v38
	v_cvt_pk_bf16_f32 v34, v34, v35
	v_cvt_pk_bf16_f32 v35, v40, v41
	global_store_dwordx4 v[44:45], v[32:35], off offset:64
	s_nop 0
	v_cndmask_b32_e64 v36, v36, v37, s[6:7]
	v_mul_f32_e32 v37, 0x37800000, v36
	v_cndmask_b32_e32 v36, v36, v37, vcc
	v_cmp_class_f32_e32 vcc, v42, v176
	s_nop 1
	v_cndmask_b32_e32 v36, v36, v42, vcc
	v_div_scale_f32 v37, s[6:7], v36, v36, v179
	v_rcp_f32_e32 v38, v37
	s_nop 0
	v_fma_f32 v32, -v37, v38, 1.0
	v_fmac_f32_e32 v38, v32, v38
	v_div_scale_f32 v32, vcc, v179, v36, v179
	v_mul_f32_e32 v33, v32, v38
	v_fma_f32 v34, -v37, v33, v32
	v_fmac_f32_e32 v33, v34, v38
	v_fma_f32 v32, -v37, v33, v32
	v_div_fmas_f32 v32, v32, v38, v33
	v_div_fixup_f32 v32, v32, v36, v179
	v_pk_mul_f32 v[24:25], v[24:25], v[32:33] op_sel_hi:[1,0]
	v_pk_mul_f32 v[26:27], v[26:27], v[32:33] op_sel_hi:[1,0]
	v_pk_mul_f32 v[28:29], v[28:29], v[32:33] op_sel_hi:[1,0]
	v_pk_mul_f32 v[30:31], v[30:31], v[32:33] op_sel_hi:[1,0]
	v_pk_mul_f32 v[34:35], v[138:139], v[26:27]
	v_pk_mul_f32 v[26:27], v[136:137], v[24:25]
	v_pk_mul_f32 v[30:31], v[142:143], v[30:31]
	v_pk_mul_f32 v[28:29], v[140:141], v[28:29]
	v_pk_mul_f32 v[36:37], v[12:13], v[12:13]
	v_cvt_pk_bf16_f32 v24, v28, v29
	v_cvt_pk_bf16_f32 v25, v30, v31
	v_cvt_pk_bf16_f32 v26, v26, v27
	v_cvt_pk_bf16_f32 v27, v34, v35
	v_pk_mul_f32 v[34:35], v[14:15], v[14:15]
	v_mul_f32_e32 v33, v0, v0
	v_pk_mov_b32 v[38:39], v[36:37], v[34:35] op_sel:[1,0]
	v_mov_b32_e32 v37, v35
	v_pk_add_f32 v[34:35], v[38:39], v[36:37]
	v_pk_mul_f32 v[36:37], v[10:11], v[10:11]
	v_pk_mul_f32 v[38:39], v[8:9], v[8:9]
	v_pk_add_f32 v[34:35], v[34:35], v[34:35] op_sel:[0,1] op_sel_hi:[1,0]
	v_pk_mov_b32 v[40:41], v[38:39], v[36:37] op_sel:[1,0]
	v_mov_b32_e32 v39, v37
	v_pk_add_f32 v[36:37], v[40:41], v[38:39]
	v_mul_f32_e32 v38, v1, v1
	v_pk_add_f32 v[36:37], v[36:37], v[36:37] op_sel:[0,1] op_sel_hi:[1,0]
	v_mov_b32_e32 v35, v33
	v_mov_b32_e32 v37, v38
	v_pk_add_f32 v[34:35], v[34:35], v[36:37]
	v_mul_f32_e32 v36, v5, v5
	v_mul_f32_e32 v39, v2, v2
	v_pk_fma_f32 v[36:37], v[4:5], v[4:5], v[36:37] op_sel_hi:[1,1,0]
	v_mul_f32_e32 v38, v7, v7
	v_mul_f32_e32 v40, v3, v3
	v_mov_b32_e32 v37, v39
	v_pk_fma_f32 v[38:39], v[6:7], v[6:7], v[38:39] op_sel_hi:[1,1,0]
	v_add_co_u32_e32 v30, vcc, s71, v120
	v_mov_b32_e32 v39, v40
	v_pk_add_f32 v[36:37], v[36:37], v[38:39]
	v_addc_co_u32_e32 v31, vcc, 0, v121, vcc
	v_pk_add_f32 v[34:35], v[34:35], v[36:37]
	global_store_dwordx4 v[30:31], v[24:27], off
	v_add_f32_e32 v33, v34, v35
	v_mov_b32_e32 v34, v33
	s_nop 1
	v_permlane16_swap_b32_e32 v34, v33
	v_pk_mul_f32 v[18:19], v[18:19], v[32:33] op_sel_hi:[1,0]
	v_pk_mul_f32 v[20:21], v[20:21], v[32:33] op_sel_hi:[1,0]
	v_pk_mul_f32 v[24:25], v[130:131], v[18:19]
	v_pk_mul_f32 v[20:21], v[132:133], v[20:21]
	s_waitcnt lgkmcnt(0)
	v_add_f32_e32 v26, v33, v34
	v_mov_b32_e32 v27, v26
	s_nop 1
	v_permlane32_swap_b32_e32 v27, v26
	v_pk_mul_f32 v[16:17], v[16:17], v[32:33] op_sel_hi:[1,0]
	v_pk_mul_f32 v[22:23], v[22:23], v[32:33] op_sel_hi:[1,0]
	v_lshl_add_u64 v[28:29], v[120:121], 0, s[16:17]
	v_pk_mul_f32 v[22:23], v[134:135], v[22:23]
	s_waitcnt lgkmcnt(0)
	v_add_f32_e32 v18, v26, v27
	v_fmamk_f32 v18, v18, 0x3c800000, v175
	v_mul_f32_e32 v19, 0x4f800000, v18
	v_cmp_gt_f32_e32 vcc, s69, v18
	s_nop 1
	v_cndmask_b32_e32 v26, v18, v19, vcc
	v_sqrt_f32_e32 v27, v26
	v_pk_mul_f32 v[18:19], v[128:129], v[16:17]
	v_cvt_pk_bf16_f32 v16, v20, v21
	v_cvt_pk_bf16_f32 v17, v22, v23
	v_add_u32_e32 v20, -1, v27
	v_fma_f32 v21, -v20, v27, v26
	v_cmp_ge_f32_e64 s[6:7], 0, v21
	v_add_u32_e32 v21, 1, v27
	v_fma_f32 v22, -v21, v27, v26
	v_cndmask_b32_e64 v20, v27, v20, s[6:7]
	v_cmp_lt_f32_e64 s[6:7], 0, v22
	v_cvt_pk_bf16_f32 v18, v18, v19
	v_cvt_pk_bf16_f32 v19, v24, v25
	global_store_dwordx4 v[28:29], v[16:19], off offset:64
	s_nop 0
	v_cndmask_b32_e64 v20, v20, v21, s[6:7]
	v_mul_f32_e32 v21, 0x37800000, v20
	v_cndmask_b32_e32 v20, v20, v21, vcc
	v_cmp_class_f32_e32 vcc, v26, v176
	s_nop 1
	v_cndmask_b32_e32 v20, v20, v26, vcc
	v_div_scale_f32 v21, s[6:7], v20, v20, v179
	v_rcp_f32_e32 v22, v21
	s_nop 0
	v_fma_f32 v16, -v21, v22, 1.0
	v_fmac_f32_e32 v22, v16, v22
	v_div_scale_f32 v16, vcc, v179, v20, v179
	v_mul_f32_e32 v17, v16, v22
	v_fma_f32 v18, -v21, v17, v16
	v_fmac_f32_e32 v17, v18, v22
	v_fma_f32 v16, -v21, v17, v16
	v_div_fmas_f32 v16, v16, v22, v17
	v_div_fixup_f32 v16, v16, v20, v179
	v_pk_mul_f32 v[14:15], v[14:15], v[16:17] op_sel_hi:[1,0]
	v_pk_mul_f32 v[12:13], v[12:13], v[16:17] op_sel_hi:[1,0]
	v_pk_mul_f32 v[14:15], v[142:143], v[14:15]
	v_pk_mul_f32 v[8:9], v[8:9], v[16:17] op_sel_hi:[1,0]
	v_pk_mul_f32 v[10:11], v[10:11], v[16:17] op_sel_hi:[1,0]
	v_pk_mul_f32 v[12:13], v[140:141], v[12:13]
	v_pk_mul_f32 v[18:19], v[138:139], v[10:11]
	v_pk_mul_f32 v[10:11], v[136:137], v[8:9]
	v_cvt_pk_bf16_f32 v8, v12, v13
	v_cvt_pk_bf16_f32 v9, v14, v15
	v_add_co_u32_e32 v14, vcc, s72, v120
	v_pk_mul_f32 v[0:1], v[0:1], v[16:17] op_sel_hi:[1,0]
	s_nop 0
	v_addc_co_u32_e32 v15, vcc, 0, v121, vcc
	v_pk_mul_f32 v[2:3], v[2:3], v[16:17] op_sel_hi:[1,0]
	v_cvt_pk_bf16_f32 v10, v10, v11
	v_cvt_pk_bf16_f32 v11, v18, v19
	v_lshl_add_u64 v[12:13], v[120:121], 0, s[18:19]
	global_store_dwordx4 v[14:15], v[8:11], off
	v_pk_mul_f32 v[4:5], v[4:5], v[16:17] op_sel_hi:[1,0]
	v_pk_mul_f32 v[6:7], v[6:7], v[16:17] op_sel_hi:[1,0]
	v_pk_mul_f32 v[8:9], v[130:131], v[2:3]
	v_pk_mul_f32 v[2:3], v[128:129], v[0:1]
	v_pk_mul_f32 v[6:7], v[134:135], v[6:7]
	v_pk_mul_f32 v[4:5], v[132:133], v[4:5]
	s_nop 0
	v_cvt_pk_bf16_f32 v0, v4, v5
	v_cvt_pk_bf16_f32 v1, v6, v7
	v_cvt_pk_bf16_f32 v2, v2, v3
	v_cvt_pk_bf16_f32 v3, v8, v9
	global_store_dwordx4 v[12:13], v[0:3], off offset:64
	s_andn2_b64 vcc, exec, s[4:5]
	s_mov_b64 s[4:5], -1
	s_cbranch_vccnz .LBB0_358
